# P1: peeled first pair-iteration of units 2..5: first two counted waits vmcnt(24) (do not wait for the previous epilogue's 16 stores) + no acc zeroing; on top of v23
# speedup vs baseline: 1.0030x; 1.0003x over previous
; #define PG8_STAGE(bufoff, gbase, voff) do { _Pragma("unroll") for (int _i = 0; _i < 2; ++_i) \
;         __builtin_amdgcn_global_load_lds((const unsigned*)((const char*)(gbase) + (voff)[_i]), (PG8_LAS unsigned*)(lds + (bufoff) + ldsw + _i * 8192), 16, 0, 0); } while (0)
; #define PG8_WAIT_V(n) asm volatile("s_waitcnt vmcnt(" #n ")" ::: "memory")
; #define PG8_BAR __builtin_amdgcn_s_barrier()
; template <class Epi, class Sched, bool ALIGN_EPI = false, bool SP2 = false>
; __device__ __forceinline__ void gemm_phase(PG8_LAS unsigned char* lds, const Gemm g, const Sched& S, const Epi& E, int wid_in) {
;     ...
;     for (int i = 0; i < 2; ++i) { int R, C; stage_rc(tid * 16 + i * 8192, R, C); const int Rb = Epi::PERM ? ((R & ~31) + perm32(R & 31)) : R;
;         voffA[i] = (unsigned)(R * K + C) * 2u; voffB[i] = (unsigned)(Rb * K + C) * 2u; }
;     const size_t kstep = (size_t)(BK * 2);
;     const size_t hstep = (size_t)HALF * K * 2;
;     const size_t tstep = 2 * hstep;
;     const unsigned ldsw = (unsigned)wid * 1024u;
;     const int aoff = lds_byte(wr * 64 + fr, fq * 8), boff = lds_byte(wc * 32 + fr, fq * 8);
;     ...
;         PG8_STAGE(PG8_SB(0, 0), cB, voffB); PG8_STAGE(PG8_SB(0, 1), cB + hstep, voffB); PG8_STAGE(PG8_SA(0, 0), cA, voffA); PG8_STAGE(PG8_SA(0, 1), cA + hstep, voffA);
;         if (wr == 1) PG8_BAR;
;         PG8_WAIT_V(2); PG8_BAR;
;         PG8_STAGE(PG8_SB(1, 0), cB + kstep, voffB); PG8_STAGE(PG8_SA(1, 0), cA + kstep, voffA); PG8_STAGE(PG8_SB(1, 1), cB + hstep + kstep, voffB);
;         PG8_WAIT_V(6); PG8_BAR;
.LBB0_221:
	s_add_u32 s14, s96, 0x3c00000
	s_addc_u32 s15, s97, 0
	s_add_u32 s16, s96, 0x5c00000
	s_addc_u32 s17, s97, 0
	s_add_u32 s20, s96, 0x8c00000
	s_addc_u32 s21, s97, 0
	s_add_u32 s22, s96, 0xcc00000
	s_addc_u32 s23, s97, 0
	s_add_u32 s64, s96, 0xd400000
	s_addc_u32 s65, s97, 0
	s_add_u32 s72, s96, 0xdc00000
	s_mov_b64 s[74:75], 0x80
	v_writelane_b32 v252, s64, 16
	s_addc_u32 s73, s97, 0
	s_bfe_u32 s1, s71, 0x20006
	s_add_i32 m0, s34, 0x18000
	v_lshl_add_u64 v[6:7], v[6:7], 0, s[74:75]
	v_writelane_b32 v252, s65, 17
	s_lshl_b32 s3, s1, 5
	s_waitcnt vmcnt(2)
	s_barrier
	global_load_lds_dwordx4 v[6:7], off
	v_lshl_add_u64 v[4:5], v[4:5], 0, s[74:75]
	s_add_i32 m0, s34, 0x1a000
	s_add_i32 s64, s34, 0x8000
	s_add_i32 s65, s34, 0xa000
	global_load_lds_dwordx4 v[4:5], off
	v_lshl_add_u64 v[0:1], v[0:1], 0, s[74:75]
	s_mov_b32 m0, s64
	s_add_u32 s70, s88, 0x40080
	global_load_lds_dwordx4 v[0:1], off
	v_lshl_add_u64 v[0:1], v[2:3], 0, s[74:75]
	s_mov_b32 m0, s65
	s_mov_b32 s5, s71
	s_addc_u32 s71, s89, 0
	global_load_lds_dwordx4 v[0:1], off
	s_add_i32 m0, s34, 0x1c000
	v_lshl_add_u64 v[0:1], s[70:71], 0, v[138:139]
	global_load_lds_dwordx4 v[0:1], off
	v_lshl_add_u64 v[0:1], s[70:71], 0, v[142:143]
	s_add_i32 m0, s34, 0x1e000
	v_and_b32_e32 v2, 48, v8
	global_load_lds_dwordx4 v[0:1], off
	v_and_b32_e32 v0, 15, v8
	v_lshl_or_b32 v168, s0, 6, v0
	v_and_b32_e32 v3, 0xfffffc00, v13
	v_lshl_or_b32 v0, v0, 6, v2
	v_lshlrev_b32_e32 v2, 2, v8
	v_ashrrev_i32_e32 v1, 4, v8
	v_lshl_add_u32 v4, s0, 13, v3
	v_and_b32_e32 v2, 32, v2
	v_lshl_add_u32 v3, s1, 12, v3
	s_cmpk_lt_u32 s5, 0x100
	v_bitop3_b32 v4, v0, v4, v2 bitop3:0xde
	v_bitop3_b32 v169, v0, v3, v2 bitop3:0xde
	s_cselect_b64 s[76:77], -1, 0
	s_bitcmp0_b32 s5, 6
	v_lshlrev_b32_e32 v0, 2, v1
	s_cselect_b64 s[0:1], -1, 0
	v_cmp_gt_i32_e32 vcc, 2, v1
	v_lshl_add_u32 v170, v1, 3, s3
	v_ashrrev_i32_e32 v1, 31, v0
	s_and_b64 s[78:79], s[0:1], vcc
	s_mov_b64 s[0:1], s[96:97]
	v_lshlrev_b64 v[0:1], 2, v[0:1]
	v_lshl_add_u64 v[0:1], s[0:1], 0, v[0:1]
	s_mov_b64 s[0:1], 0x100000
	v_lshl_add_u64 v[146:147], v[0:1], 0, s[0:1]
	s_mov_b64 s[0:1], 0x140000
	v_lshl_add_u64 v[148:149], v[0:1], 0, s[0:1]
	v_lshlrev_b32_e32 v0, 14, v9
	v_and_b32_e32 v0, 0xffff8000, v0
	v_lshl_add_u32 v0, v10, 11, v0
	v_and_b32_e32 v1, 1, v9
	v_lshl_or_b32 v0, v1, 6, v0
	v_lshl_add_u32 v150, v11, 1, v0
	v_lshlrev_b32_e32 v0, 14, v12
	v_and_b32_e32 v0, 0xffff8000, v0
	s_waitcnt vmcnt(6)
	v_readlane_b32 s3, v252, 2
	v_lshl_add_u32 v0, v14, 11, v0
	v_and_b32_e32 v1, 1, v12
	s_ashr_i32 s96, s3, 31
	v_readlane_b32 s3, v252, 3
	v_lshl_or_b32 v0, v1, 6, v0
	s_add_i32 s70, 0, 0x10000
	s_add_i32 s71, 0, 0x14000
	s_ashr_i32 s97, s3, 31
	v_mov_b32_e32 v151, v145
	v_lshl_add_u32 v152, v15, 1, v0
	v_mov_b32_e32 v153, v145
	v_mov_b64_e32 v[154:155], 0x500
	v_mov_b64_e32 v[156:157], 0x4ff
	v_add_u32_e32 v171, s70, v169
	v_add_u32_e32 v172, s71, v169
	v_add_u32_e32 v173, 0, v4
	s_barrier
	s_mov_b32 s98, 0
	s_branch .LBB0_224

; #define PG8_BAR __builtin_amdgcn_s_barrier()
; template <class Epi, class Sched, bool ALIGN_EPI = false, bool SP2 = false>
; __device__ __forceinline__ void gemm_phase(PG8_LAS unsigned char* lds, const Gemm g, const Sched& S, const Epi& E, int wid_in) {
;     ...
;         if constexpr (ALIGN_EPI) { if (wr == 0) PG8_BAR; }
;         if constexpr (!Epi::AFTER_DRAIN) { E(acc, cur, wr, wc, fr, fq); S.done(cur); }
;         if (!has_next) break;
; #pragma unroll
;         for (int a = 0; a < 2; ++a)
; #pragma unroll
;             for (int b = 0; b < 2; ++b)
; #pragma unroll
;                 for (int m = 0; m < 4; ++m)
; #pragma unroll
;                     for (int n = 0; n < 2; ++n) acc[a][b][m][n] = (f32x4){0.f, 0.f, 0.f, 0.f};
;         cur = nxt; cA = nA; cB = nB; ++ui;
;         if constexpr (ALIGN_EPI) { if (wr == 1) PG8_BAR; }
.LBB0_223:
	s_mov_b32 s98, 1
	s_andn2_b64 vcc, exec, s[0:1]
	s_mov_b32 s4, s80
	s_mov_b32 s2, s82
	s_mov_b64 s[88:89], s[86:87]
	s_mov_b64 s[68:69], s[84:85]
	s_cbranch_vccz .LBB0_331

; #define PG8_STAGE(bufoff, gbase, voff) do { _Pragma("unroll") for (int _i = 0; _i < 2; ++_i) \
;         __builtin_amdgcn_global_load_lds((const unsigned*)((const char*)(gbase) + (voff)[_i]), (PG8_LAS unsigned*)(lds + (bufoff) + ldsw + _i * 8192), 16, 0, 0); } while (0)
; #define PG8_LDA(dst, b, h) do { _Pragma("unroll") for (int m = 0; m < 4; ++m) _Pragma("unroll") for (int k = 0; k < 2; ++k) dst[m][k] = *(const PG8_LAS bf16x8*)(lds + PG8_SA(b, h) + aoff + m * 2048 + k * 1024); } while (0)
; #define PG8_LDB(dst, b, h) do { _Pragma("unroll") for (int n = 0; n < 2; ++n) _Pragma("unroll") for (int k = 0; k < 2; ++k) dst[n][k] = *(const PG8_LAS bf16x8*)(lds + PG8_SB(b, h) + boff + n * 2048 + k * 1024); } while (0)
; #define PG8_SCHED __builtin_amdgcn_sched_barrier(0)
; template <class Epi, class Sched, bool ALIGN_EPI = false, bool SP2 = false>
; __device__ __forceinline__ void gemm_phase(PG8_LAS unsigned char* lds, const Gemm g, const Sched& S, const Epi& E, int wid_in) {
;     ...
;         const bool has_next = S.next(ui + 1, nxt);
;         const char* nA = has_next ? (const char*)g.A + (size_t)nxt.pm * tstep : cA; const char* nB = has_next ? (const char*)g.Bt + (size_t)nxt.pn * tstep : cB;
;         for (int t = 0; t < nt; t += 2) {
;             const bool last = (t == nt - 2);
;             if constexpr (Epi::HAS_MID) { if (t == nt / 2) E.mid(acc, cur, wr, wc, fr, fq); }
;             const char* a1 = cA + (size_t)(t + 1) * kstep;
;             const char* a2 = last ? nA : cA + (size_t)(t + 2) * kstep; const char* b2 = last ? nB : cB + (size_t)(t + 2) * kstep;
;             const char* a3 = a2 + kstep; const char* b3 = b2 + kstep;
;             if (last && has_next) S.a_ready(nxt);
;             if constexpr (SP2) {
;             PG8_LDB(B0, 0, 0); PG8_LDB(B1, 0, 1); PG8_SCHED; PG8_LDA(At, 0, 0); PG8_STAGE(PG8_SA(1, 1), a1 + hstep, voffA);
.LBB0_226:
	s_ashr_i32 s83, s82, 31
	s_lshl_b64 s[84:85], s[82:83], 19
	s_add_u32 s84, s8, s84
	s_addc_u32 s85, s9, s85
	s_and_b64 s[86:87], s[0:1], exec
	s_cselect_b32 s3, s85, s69
	s_cselect_b32 s5, s84, s68
	s_ashr_i32 s81, s80, 31
	s_lshl_b64 s[86:87], s[80:81], 19
	s_add_u32 s86, s13, s86
	s_addc_u32 s87, s33, s87
	s_and_b64 s[90:91], s[0:1], exec
	s_cselect_b32 s81, s87, s89
	s_cselect_b32 s83, s86, s88
	s_add_u32 s68, s68, 0x40080
	s_addc_u32 s69, s69, 0
	s_add_u32 s92, s88, 0x100
	s_addc_u32 s93, s89, 0
	s_mov_b32 s94, -2
	ds_read_b128 v[128:131], v171
	ds_read_b128 v[132:135], v171 offset:1024
	ds_read_b128 v[158:161], v171 offset:2048
	ds_read_b128 v[162:165], v171 offset:3072
	ds_read_b128 v[174:177], v172
	ds_read_b128 v[178:181], v172 offset:1024
	ds_read_b128 v[182:185], v172 offset:2048
	ds_read_b128 v[186:189], v172 offset:3072
	s_add_u32 s88, s68, 0xfffc0080
	s_addc_u32 s89, s69, -1
	s_cmp_eq_u32 s94, 12
	s_cselect_b32 s91, s3, s89
	s_cselect_b32 s90, s5, s88
	s_cselect_b32 s89, s81, s93
	s_cselect_b32 s88, s83, s92
	v_lshl_add_u64 v[166:167], s[68:69], 0, v[150:151]
	s_add_i32 m0, s34, 0xc000
	ds_read_b128 v[190:193], v173
	ds_read_b128 v[194:197], v173 offset:1024
	ds_read_b128 v[198:201], v173 offset:2048
	ds_read_b128 v[202:205], v173 offset:3072
	ds_read_b128 v[206:209], v173 offset:4096
	ds_read_b128 v[210:213], v173 offset:5120
	ds_read_b128 v[214:217], v173 offset:6144
	ds_read_b128 v[218:221], v173 offset:7168
	global_load_lds_dwordx4 v[166:167], off
	v_lshl_add_u64 v[166:167], s[68:69], 0, v[152:153]
	s_add_i32 m0, s34, 0xe000
	s_nop 0
	global_load_lds_dwordx4 v[166:167], off
	s_cmp_eq_u32 s98, 1
	s_cbranch_scc1 .Lp1ss_w0a
	s_waitcnt vmcnt(8)
	s_branch .Lp1ss_w0b

; #define PG8_STAGE(bufoff, gbase, voff) do { _Pragma("unroll") for (int _i = 0; _i < 2; ++_i) \
;         __builtin_amdgcn_global_load_lds((const unsigned*)((const char*)(gbase) + (voff)[_i]), (PG8_LAS unsigned*)(lds + (bufoff) + ldsw + _i * 8192), 16, 0, 0); } while (0)
; #define PG8_LDA(dst, b, h) do { _Pragma("unroll") for (int m = 0; m < 4; ++m) _Pragma("unroll") for (int k = 0; k < 2; ++k) dst[m][k] = *(const PG8_LAS bf16x8*)(lds + PG8_SA(b, h) + aoff + m * 2048 + k * 1024); } while (0)
; #define PG8_MMA(ai, bj, At, Bt) do { __builtin_amdgcn_s_setprio(1); _Pragma("unroll") for (int m = 0; m < 4; ++m) _Pragma("unroll") for (int n = 0; n < 2; ++n) _Pragma("unroll") for (int k = 0; k < 2; ++k) \
;         acc[ai][bj][m][n] = __builtin_amdgcn_mfma_f32_16x16x32_bf16(Bt[n][k], At[m][k], acc[ai][bj][m][n], 0, 0, 0); __builtin_amdgcn_s_setprio(0); } while (0)
; #define PG8_WAIT_V(n) asm volatile("s_waitcnt vmcnt(" #n ")" ::: "memory")
; #define PG8_WAIT_L(n) asm volatile("s_waitcnt lgkmcnt(" #n ")" ::: "memory")
; #define PG8_BAR __builtin_amdgcn_s_barrier()
; #define PG8_SCHED __builtin_amdgcn_sched_barrier(0)
; template <class Epi, class Sched, bool ALIGN_EPI = false, bool SP2 = false>
; __device__ __forceinline__ void gemm_phase(PG8_LAS unsigned char* lds, const Gemm g, const Sched& S, const Epi& E, int wid_in) {
;     ...
;             PG8_WAIT_V(8); PG8_WAIT_L(0); PG8_BAR; PG8_MMA(0, 0, At, B0); PG8_MMA(0, 1, At, B1); PG8_BAR; PG8_SCHED;
;             PG8_LDA(At, 0, 1); PG8_STAGE(PG8_SB(0, 0), b2, voffB); PG8_STAGE(PG8_SB(0, 1), b2 + hstep, voffB); PG8_STAGE(PG8_SA(0, 0), a2, voffA);
.Lp1ss_w0b:
	s_waitcnt lgkmcnt(0)
	s_barrier
	s_setprio 1
	s_waitcnt lgkmcnt(0)
	v_mfma_f32_16x16x32_bf16 v[124:127], v[128:131], v[190:193], 0
	v_mfma_f32_16x16x32_bf16 v[120:123], v[158:161], v[190:193], 0
	v_mfma_f32_16x16x32_bf16 v[108:111], v[128:131], v[198:201], 0
	v_mfma_f32_16x16x32_bf16 v[104:107], v[158:161], v[198:201], 0
	v_mfma_f32_16x16x32_bf16 v[92:95], v[128:131], v[206:209], 0
	v_mfma_f32_16x16x32_bf16 v[88:91], v[158:161], v[206:209], 0
	v_mfma_f32_16x16x32_bf16 v[76:79], v[128:131], v[214:217], 0
	v_mfma_f32_16x16x32_bf16 v[72:75], v[158:161], v[214:217], 0
	v_mfma_f32_16x16x32_bf16 v[124:127], v[132:135], v[194:197], v[124:127]
	v_mfma_f32_16x16x32_bf16 v[120:123], v[162:165], v[194:197], v[120:123]
	v_mfma_f32_16x16x32_bf16 v[108:111], v[132:135], v[202:205], v[108:111]
	v_mfma_f32_16x16x32_bf16 v[104:107], v[162:165], v[202:205], v[104:107]
	v_mfma_f32_16x16x32_bf16 v[92:95], v[132:135], v[210:213], v[92:95]
	v_mfma_f32_16x16x32_bf16 v[88:91], v[162:165], v[210:213], v[88:91]
	v_mfma_f32_16x16x32_bf16 v[76:79], v[132:135], v[218:221], v[76:79]
	v_mfma_f32_16x16x32_bf16 v[72:75], v[162:165], v[218:221], v[72:75]
	s_setprio 0
	s_setprio 1
	v_mfma_f32_16x16x32_bf16 v[116:119], v[174:177], v[190:193], 0
	v_mfma_f32_16x16x32_bf16 v[112:115], v[182:185], v[190:193], 0
	v_mfma_f32_16x16x32_bf16 v[100:103], v[174:177], v[198:201], 0
	v_mfma_f32_16x16x32_bf16 v[96:99], v[182:185], v[198:201], 0
	v_mfma_f32_16x16x32_bf16 v[84:87], v[174:177], v[206:209], 0
	v_mfma_f32_16x16x32_bf16 v[80:83], v[182:185], v[206:209], 0
	v_mfma_f32_16x16x32_bf16 v[68:71], v[174:177], v[214:217], 0
	v_mfma_f32_16x16x32_bf16 v[64:67], v[182:185], v[214:217], 0
	v_mfma_f32_16x16x32_bf16 v[116:119], v[178:181], v[194:197], v[116:119]
	v_mfma_f32_16x16x32_bf16 v[112:115], v[186:189], v[194:197], v[112:115]
	v_mfma_f32_16x16x32_bf16 v[100:103], v[178:181], v[202:205], v[100:103]
	v_mfma_f32_16x16x32_bf16 v[96:99], v[186:189], v[202:205], v[96:99]
	v_mfma_f32_16x16x32_bf16 v[84:87], v[178:181], v[210:213], v[84:87]
	v_mfma_f32_16x16x32_bf16 v[80:83], v[186:189], v[210:213], v[80:83]
	v_mfma_f32_16x16x32_bf16 v[68:71], v[178:181], v[218:221], v[68:71]
	v_mfma_f32_16x16x32_bf16 v[64:67], v[186:189], v[218:221], v[64:67]
	s_setprio 0
	s_barrier
	s_add_i32 s95, s70, s12
	v_lshl_add_u64 v[166:167], s[88:89], 0, v[138:139]
	s_mov_b32 m0, s95
	ds_read_b128 v[190:193], v173 offset:16384
	ds_read_b128 v[194:197], v173 offset:17408
	ds_read_b128 v[198:201], v173 offset:18432
	ds_read_b128 v[202:205], v173 offset:19456
	ds_read_b128 v[206:209], v173 offset:20480
	ds_read_b128 v[210:213], v173 offset:21504
	ds_read_b128 v[214:217], v173 offset:22528
	ds_read_b128 v[218:221], v173 offset:23552
	global_load_lds_dwordx4 v[166:167], off
	s_add_i32 m0, s95, 0x2000
	s_add_u32 vcc_lo, s88, 0x40000
	v_lshl_add_u64 v[222:223], s[88:89], 0, v[142:143]
	s_addc_u32 vcc_hi, s89, 0
	s_add_i32 s95, s71, s12
	global_load_lds_dwordx4 v[222:223], off
	v_lshl_add_u64 v[224:225], vcc, 0, v[138:139]
	s_mov_b32 m0, s95
	v_lshl_add_u64 v[226:227], s[90:91], 0, v[140:141]
	global_load_lds_dwordx4 v[224:225], off
	v_lshl_add_u64 v[224:225], vcc, 0, v[142:143]
	s_add_i32 m0, s95, 0x2000
	s_nop 0
	global_load_lds_dwordx4 v[224:225], off
	v_lshl_add_u64 v[224:225], s[90:91], 0, v[136:137]
	s_mov_b32 m0, s34
	s_nop 0
	global_load_lds_dwordx4 v[224:225], off
	s_mov_b32 m0, s35
	s_nop 0
	global_load_lds_dwordx4 v[226:227], off
	s_cmp_eq_u32 s98, 1
	s_cbranch_scc1 .Lp1ss_w1a
	s_waitcnt vmcnt(8)
	s_branch .Lp1ss_w1b

; #define PG8_STAGE(bufoff, gbase, voff) do { _Pragma("unroll") for (int _i = 0; _i < 2; ++_i) \
;         __builtin_amdgcn_global_load_lds((const unsigned*)((const char*)(gbase) + (voff)[_i]), (PG8_LAS unsigned*)(lds + (bufoff) + ldsw + _i * 8192), 16, 0, 0); } while (0)
; #define PG8_LDA(dst, b, h) do { _Pragma("unroll") for (int m = 0; m < 4; ++m) _Pragma("unroll") for (int k = 0; k < 2; ++k) dst[m][k] = *(const PG8_LAS bf16x8*)(lds + PG8_SA(b, h) + aoff + m * 2048 + k * 1024); } while (0)
; #define PG8_LDB(dst, b, h) do { _Pragma("unroll") for (int n = 0; n < 2; ++n) _Pragma("unroll") for (int k = 0; k < 2; ++k) dst[n][k] = *(const PG8_LAS bf16x8*)(lds + PG8_SB(b, h) + boff + n * 2048 + k * 1024); } while (0)
; #define PG8_MMA(ai, bj, At, Bt) do { __builtin_amdgcn_s_setprio(1); _Pragma("unroll") for (int m = 0; m < 4; ++m) _Pragma("unroll") for (int n = 0; n < 2; ++n) _Pragma("unroll") for (int k = 0; k < 2; ++k) \
;         acc[ai][bj][m][n] = __builtin_amdgcn_mfma_f32_16x16x32_bf16(Bt[n][k], At[m][k], acc[ai][bj][m][n], 0, 0, 0); __builtin_amdgcn_s_setprio(0); } while (0)
; #define PG8_WAIT_V(n) asm volatile("s_waitcnt vmcnt(" #n ")" ::: "memory")
; #define PG8_WAIT_L(n) asm volatile("s_waitcnt lgkmcnt(" #n ")" ::: "memory")
; #define PG8_BAR __builtin_amdgcn_s_barrier()
; #define PG8_SCHED __builtin_amdgcn_sched_barrier(0)
; template <class Epi, class Sched, bool ALIGN_EPI = false, bool SP2 = false>
; __device__ __forceinline__ void gemm_phase(PG8_LAS unsigned char* lds, const Gemm g, const Sched& S, const Epi& E, int wid_in) {
;     ...
;             PG8_WAIT_V(8); PG8_WAIT_L(0); PG8_BAR; PG8_MMA(1, 0, At, B0); PG8_MMA(1, 1, At, B1); PG8_BAR; PG8_SCHED;
;             PG8_LDB(B0, 1, 0); PG8_LDB(B1, 1, 1); PG8_SCHED; PG8_LDA(At, 1, 0); PG8_STAGE(PG8_SA(0, 1), a2 + hstep, voffA);
;             PG8_WAIT_V(8); PG8_WAIT_L(0); PG8_BAR; PG8_MMA(0, 0, At, B0); PG8_MMA(0, 1, At, B1); PG8_BAR; PG8_SCHED;
.Lp1ss_w1b:
	s_waitcnt lgkmcnt(0)
	s_barrier
	s_setprio 1
	s_waitcnt lgkmcnt(0)
	v_mfma_f32_16x16x32_bf16 v[60:63], v[128:131], v[190:193], 0
	v_mfma_f32_16x16x32_bf16 v[56:59], v[158:161], v[190:193], 0
	v_mfma_f32_16x16x32_bf16 v[44:47], v[128:131], v[198:201], 0
	v_mfma_f32_16x16x32_bf16 v[40:43], v[158:161], v[198:201], 0
	v_mfma_f32_16x16x32_bf16 v[28:31], v[128:131], v[206:209], 0
	v_mfma_f32_16x16x32_bf16 v[24:27], v[158:161], v[206:209], 0
	v_mfma_f32_16x16x32_bf16 v[12:15], v[128:131], v[214:217], 0
	v_mfma_f32_16x16x32_bf16 v[8:11], v[158:161], v[214:217], 0
	v_mfma_f32_16x16x32_bf16 v[60:63], v[132:135], v[194:197], v[60:63]
	v_mfma_f32_16x16x32_bf16 v[56:59], v[162:165], v[194:197], v[56:59]
	v_mfma_f32_16x16x32_bf16 v[44:47], v[132:135], v[202:205], v[44:47]
	v_mfma_f32_16x16x32_bf16 v[40:43], v[162:165], v[202:205], v[40:43]
	v_mfma_f32_16x16x32_bf16 v[28:31], v[132:135], v[210:213], v[28:31]
	v_mfma_f32_16x16x32_bf16 v[24:27], v[162:165], v[210:213], v[24:27]
	v_mfma_f32_16x16x32_bf16 v[12:15], v[132:135], v[218:221], v[12:15]
	v_mfma_f32_16x16x32_bf16 v[8:11], v[162:165], v[218:221], v[8:11]
	s_setprio 0
	s_setprio 1
	v_mfma_f32_16x16x32_bf16 v[52:55], v[174:177], v[190:193], 0
	v_mfma_f32_16x16x32_bf16 v[48:51], v[182:185], v[190:193], 0
	v_mfma_f32_16x16x32_bf16 v[36:39], v[174:177], v[198:201], 0
	v_mfma_f32_16x16x32_bf16 v[32:35], v[182:185], v[198:201], 0
	v_mfma_f32_16x16x32_bf16 v[20:23], v[174:177], v[206:209], 0
	v_mfma_f32_16x16x32_bf16 v[16:19], v[182:185], v[206:209], 0
	v_mfma_f32_16x16x32_bf16 v[4:7], v[174:177], v[214:217], 0
	v_mfma_f32_16x16x32_bf16 v[0:3], v[182:185], v[214:217], 0
	v_mfma_f32_16x16x32_bf16 v[52:55], v[178:181], v[194:197], v[52:55]
	v_mfma_f32_16x16x32_bf16 v[48:51], v[186:189], v[194:197], v[48:51]
	v_mfma_f32_16x16x32_bf16 v[36:39], v[178:181], v[202:205], v[36:39]
	v_mfma_f32_16x16x32_bf16 v[32:35], v[186:189], v[202:205], v[32:35]
	v_mfma_f32_16x16x32_bf16 v[20:23], v[178:181], v[210:213], v[20:23]
	v_mfma_f32_16x16x32_bf16 v[16:19], v[186:189], v[210:213], v[16:19]
	v_mfma_f32_16x16x32_bf16 v[4:7], v[178:181], v[218:221], v[4:7]
	v_mfma_f32_16x16x32_bf16 v[0:3], v[186:189], v[218:221], v[0:3]
	s_setprio 0
	s_barrier
	s_add_i32 s95, 0, 0x18000
	v_add_u32_e32 v144, s95, v169
	s_add_i32 vcc_lo, 0, 0x1c000
	ds_read_b128 v[128:131], v144
	ds_read_b128 v[132:135], v144 offset:1024
	ds_read_b128 v[158:161], v144 offset:2048
	ds_read_b128 v[162:165], v144 offset:3072
	v_add_u32_e32 v144, vcc_lo, v169
	ds_read_b128 v[174:177], v144
	ds_read_b128 v[178:181], v144 offset:1024
	ds_read_b128 v[182:185], v144 offset:2048
	ds_read_b128 v[186:189], v144 offset:3072
	s_add_u32 s90, s90, 0x40000
	s_addc_u32 s91, s91, 0
	s_mov_b32 m0, s61
	v_lshl_add_u64 v[228:229], s[90:91], 0, v[136:137]
	ds_read_b128 v[190:193], v173 offset:32768
	ds_read_b128 v[194:197], v173 offset:33792
	ds_read_b128 v[198:201], v173 offset:34816
	ds_read_b128 v[202:205], v173 offset:35840
	ds_read_b128 v[206:209], v173 offset:36864
	ds_read_b128 v[210:213], v173 offset:37888
	ds_read_b128 v[214:217], v173 offset:38912
	ds_read_b128 v[218:221], v173 offset:39936
	global_load_lds_dwordx4 v[228:229], off
	v_lshl_add_u64 v[228:229], s[90:91], 0, v[140:141]
	s_mov_b32 m0, s62
	s_nop 0
	global_load_lds_dwordx4 v[228:229], off
	s_waitcnt vmcnt(8)
	s_waitcnt lgkmcnt(0)
	s_barrier
	s_setprio 1
	s_waitcnt lgkmcnt(0)
	v_mfma_f32_16x16x32_bf16 v[124:127], v[128:131], v[190:193], v[124:127]
	v_mfma_f32_16x16x32_bf16 v[120:123], v[158:161], v[190:193], v[120:123]
	v_mfma_f32_16x16x32_bf16 v[108:111], v[128:131], v[198:201], v[108:111]
	v_mfma_f32_16x16x32_bf16 v[104:107], v[158:161], v[198:201], v[104:107]
	v_mfma_f32_16x16x32_bf16 v[92:95], v[128:131], v[206:209], v[92:95]
	v_mfma_f32_16x16x32_bf16 v[88:91], v[158:161], v[206:209], v[88:91]
	v_mfma_f32_16x16x32_bf16 v[76:79], v[128:131], v[214:217], v[76:79]
	v_mfma_f32_16x16x32_bf16 v[72:75], v[158:161], v[214:217], v[72:75]
	v_mfma_f32_16x16x32_bf16 v[124:127], v[132:135], v[194:197], v[124:127]
	v_mfma_f32_16x16x32_bf16 v[120:123], v[162:165], v[194:197], v[120:123]
	v_mfma_f32_16x16x32_bf16 v[108:111], v[132:135], v[202:205], v[108:111]
	v_mfma_f32_16x16x32_bf16 v[104:107], v[162:165], v[202:205], v[104:107]
	v_mfma_f32_16x16x32_bf16 v[92:95], v[132:135], v[210:213], v[92:95]
	v_mfma_f32_16x16x32_bf16 v[88:91], v[162:165], v[210:213], v[88:91]
	v_mfma_f32_16x16x32_bf16 v[76:79], v[132:135], v[218:221], v[76:79]
	v_mfma_f32_16x16x32_bf16 v[72:75], v[162:165], v[218:221], v[72:75]
	s_setprio 0
	s_setprio 1
	v_mfma_f32_16x16x32_bf16 v[116:119], v[174:177], v[190:193], v[116:119]
	v_mfma_f32_16x16x32_bf16 v[112:115], v[182:185], v[190:193], v[112:115]
	v_mfma_f32_16x16x32_bf16 v[100:103], v[174:177], v[198:201], v[100:103]
	v_mfma_f32_16x16x32_bf16 v[96:99], v[182:185], v[198:201], v[96:99]
	v_mfma_f32_16x16x32_bf16 v[84:87], v[174:177], v[206:209], v[84:87]
	v_mfma_f32_16x16x32_bf16 v[80:83], v[182:185], v[206:209], v[80:83]
	v_mfma_f32_16x16x32_bf16 v[68:71], v[174:177], v[214:217], v[68:71]
	v_mfma_f32_16x16x32_bf16 v[64:67], v[182:185], v[214:217], v[64:67]
	v_mfma_f32_16x16x32_bf16 v[116:119], v[178:181], v[194:197], v[116:119]
	v_mfma_f32_16x16x32_bf16 v[112:115], v[186:189], v[194:197], v[112:115]
	v_mfma_f32_16x16x32_bf16 v[100:103], v[178:181], v[202:205], v[100:103]
	v_mfma_f32_16x16x32_bf16 v[96:99], v[186:189], v[202:205], v[96:99]
	v_mfma_f32_16x16x32_bf16 v[84:87], v[178:181], v[210:213], v[84:87]
	v_mfma_f32_16x16x32_bf16 v[80:83], v[186:189], v[210:213], v[80:83]
	v_mfma_f32_16x16x32_bf16 v[68:71], v[178:181], v[218:221], v[68:71]
	v_mfma_f32_16x16x32_bf16 v[64:67], v[186:189], v[218:221], v[64:67]
	s_setprio 0
	s_barrier
; #define PG8_STAGE(bufoff, gbase, voff) do { _Pragma("unroll") for (int _i = 0; _i < 2; ++_i) \
;         __builtin_amdgcn_global_load_lds((const unsigned*)((const char*)(gbase) + (voff)[_i]), (PG8_LAS unsigned*)(lds + (bufoff) + ldsw + _i * 8192), 16, 0, 0); } while (0)
; #define PG8_LDA(dst, b, h) do { _Pragma("unroll") for (int m = 0; m < 4; ++m) _Pragma("unroll") for (int k = 0; k < 2; ++k) dst[m][k] = *(const PG8_LAS bf16x8*)(lds + PG8_SA(b, h) + aoff + m * 2048 + k * 1024); } while (0)
; #define PG8_MMA(ai, bj, At, Bt) do { __builtin_amdgcn_s_setprio(1); _Pragma("unroll") for (int m = 0; m < 4; ++m) _Pragma("unroll") for (int n = 0; n < 2; ++n) _Pragma("unroll") for (int k = 0; k < 2; ++k) \
;         acc[ai][bj][m][n] = __builtin_amdgcn_mfma_f32_16x16x32_bf16(Bt[n][k], At[m][k], acc[ai][bj][m][n], 0, 0, 0); __builtin_amdgcn_s_setprio(0); } while (0)
; #define PG8_WAIT_V(n) asm volatile("s_waitcnt vmcnt(" #n ")" ::: "memory")
; #define PG8_WAIT_L(n) asm volatile("s_waitcnt lgkmcnt(" #n ")" ::: "memory")
; #define PG8_BAR __builtin_amdgcn_s_barrier()
; #define PG8_SCHED __builtin_amdgcn_sched_barrier(0)
; template <class Epi, class Sched, bool ALIGN_EPI = false, bool SP2 = false>
; __device__ __forceinline__ void gemm_phase(PG8_LAS unsigned char* lds, const Gemm g, const Sched& S, const Epi& E, int wid_in) {
;     ...
;         for (int t = 0; t < nt; t += 2) {
;     ...
;             PG8_LDA(At, 1, 1); PG8_STAGE(PG8_SB(1, 0), b3, voffB); PG8_STAGE(PG8_SB(1, 1), b3 + hstep, voffB); PG8_STAGE(PG8_SA(1, 0), a3, voffA);
;             PG8_WAIT_V(8); PG8_WAIT_L(0); PG8_BAR; PG8_MMA(1, 0, At, B0); PG8_MMA(1, 1, At, B1); PG8_BAR; PG8_SCHED;
	s_add_i32 s90, s95, s12
	v_lshl_add_u64 v[166:167], v[166:167], 0, s[74:75]
	s_mov_b32 m0, s90
	ds_read_b128 v[190:193], v173 offset:49152
	ds_read_b128 v[194:197], v173 offset:50176
	ds_read_b128 v[198:201], v173 offset:51200
	ds_read_b128 v[202:205], v173 offset:52224
	ds_read_b128 v[206:209], v173 offset:53248
	ds_read_b128 v[210:213], v173 offset:54272
	ds_read_b128 v[214:217], v173 offset:55296
	ds_read_b128 v[218:221], v173 offset:56320
	global_load_lds_dwordx4 v[166:167], off
	s_add_i32 m0, s90, 0x2000
	s_add_u32 s88, s88, 0x40080
	v_lshl_add_u64 v[166:167], v[222:223], 0, s[74:75]
	s_addc_u32 s89, s89, 0
	s_add_i32 s90, vcc_lo, s12
	global_load_lds_dwordx4 v[166:167], off
	v_lshl_add_u64 v[166:167], s[88:89], 0, v[138:139]
	s_mov_b32 m0, s90
	s_nop 0
	global_load_lds_dwordx4 v[166:167], off
	v_lshl_add_u64 v[166:167], s[88:89], 0, v[142:143]
	s_add_i32 m0, s90, 0x2000
	s_nop 0
	global_load_lds_dwordx4 v[166:167], off
	v_lshl_add_u64 v[166:167], v[224:225], 0, s[74:75]
	s_mov_b32 m0, s64
	s_nop 0
	global_load_lds_dwordx4 v[166:167], off
	v_lshl_add_u64 v[166:167], v[226:227], 0, s[74:75]
	s_mov_b32 m0, s65
	s_nop 0
	global_load_lds_dwordx4 v[166:167], off
	s_waitcnt vmcnt(8)
	s_waitcnt lgkmcnt(0)
	s_barrier
	s_setprio 1
	s_waitcnt lgkmcnt(0)
	v_mfma_f32_16x16x32_bf16 v[60:63], v[128:131], v[190:193], v[60:63]
	v_mfma_f32_16x16x32_bf16 v[56:59], v[158:161], v[190:193], v[56:59]
	v_mfma_f32_16x16x32_bf16 v[44:47], v[128:131], v[198:201], v[44:47]
	v_mfma_f32_16x16x32_bf16 v[40:43], v[158:161], v[198:201], v[40:43]
	v_mfma_f32_16x16x32_bf16 v[28:31], v[128:131], v[206:209], v[28:31]
	v_mfma_f32_16x16x32_bf16 v[24:27], v[158:161], v[206:209], v[24:27]
	v_mfma_f32_16x16x32_bf16 v[12:15], v[128:131], v[214:217], v[12:15]
	v_mfma_f32_16x16x32_bf16 v[8:11], v[158:161], v[214:217], v[8:11]
	v_mfma_f32_16x16x32_bf16 v[60:63], v[132:135], v[194:197], v[60:63]
	v_mfma_f32_16x16x32_bf16 v[56:59], v[162:165], v[194:197], v[56:59]
	v_mfma_f32_16x16x32_bf16 v[44:47], v[132:135], v[202:205], v[44:47]
	v_mfma_f32_16x16x32_bf16 v[40:43], v[162:165], v[202:205], v[40:43]
	v_mfma_f32_16x16x32_bf16 v[28:31], v[132:135], v[210:213], v[28:31]
	v_mfma_f32_16x16x32_bf16 v[24:27], v[162:165], v[210:213], v[24:27]
	v_mfma_f32_16x16x32_bf16 v[12:15], v[132:135], v[218:221], v[12:15]
	v_mfma_f32_16x16x32_bf16 v[8:11], v[162:165], v[218:221], v[8:11]
	s_setprio 0
	s_setprio 1
	v_mfma_f32_16x16x32_bf16 v[52:55], v[174:177], v[190:193], v[52:55]
	v_mfma_f32_16x16x32_bf16 v[48:51], v[182:185], v[190:193], v[48:51]
	v_mfma_f32_16x16x32_bf16 v[36:39], v[174:177], v[198:201], v[36:39]
	v_mfma_f32_16x16x32_bf16 v[32:35], v[182:185], v[198:201], v[32:35]
	v_mfma_f32_16x16x32_bf16 v[20:23], v[174:177], v[206:209], v[20:23]
	v_mfma_f32_16x16x32_bf16 v[16:19], v[182:185], v[206:209], v[16:19]
	v_mfma_f32_16x16x32_bf16 v[4:7], v[174:177], v[214:217], v[4:7]
	v_mfma_f32_16x16x32_bf16 v[0:3], v[182:185], v[214:217], v[0:3]
	v_mfma_f32_16x16x32_bf16 v[52:55], v[178:181], v[194:197], v[52:55]
	v_mfma_f32_16x16x32_bf16 v[48:51], v[186:189], v[194:197], v[48:51]
	v_mfma_f32_16x16x32_bf16 v[36:39], v[178:181], v[202:205], v[36:39]
	v_mfma_f32_16x16x32_bf16 v[32:35], v[186:189], v[202:205], v[32:35]
	v_mfma_f32_16x16x32_bf16 v[20:23], v[178:181], v[210:213], v[20:23]
	v_mfma_f32_16x16x32_bf16 v[16:19], v[186:189], v[210:213], v[16:19]
	v_mfma_f32_16x16x32_bf16 v[4:7], v[178:181], v[218:221], v[4:7]
	v_mfma_f32_16x16x32_bf16 v[0:3], v[186:189], v[218:221], v[0:3]
	s_setprio 0
	s_barrier
	s_add_i32 s94, s94, 2
	s_add_u32 s68, s68, 0x100
	s_addc_u32 s69, s69, 0
	s_add_u32 s92, s92, 0x100
	s_addc_u32 s93, s93, 0
	s_cmp_gt_u32 s94, 13
